# skinny section no longer drains the tile epilogue stores before issuing its loads (vmcnt(0) removed where no LDS-DMA is outstanding)
# speedup vs baseline: 1.0151x; 1.0029x over previous
.LBB0_951:
	v_readlane_b32 s66, v254, 1
	v_readlane_b32 s52, v253, 61
	v_readlane_b32 s67, v254, 2
	v_readlane_b32 s50, v254, 22
	v_readlane_b32 s53, v253, 62
	v_readlane_b32 s68, v254, 3
	v_readlane_b32 s69, v254, 4
	s_movk_i32 s70, 0x1000
	v_readlane_b32 s44, v254, 8
	v_readlane_b32 s45, v254, 9
	s_mov_b32 s71, 0x20000
	s_mov_b32 s73, 0x1ffff
	s_mov_b32 s87, 0x800000
	s_mov_b32 s74, 0x50000
	s_mov_b32 s75, 0xe000
	s_movk_i32 s78, 0x3000
	s_movk_i32 s79, 0x5000
	s_movk_i32 s80, 0x7000
	s_mov_b32 s81, 0x8000
	s_mov_b32 s59, 0xa000
	s_mov_b32 s67, 0xc000
	s_mov_b32 s64, 0xf000
	v_readlane_b32 s51, v254, 23
	v_readlane_b32 s62, v254, 49
	v_readlane_b32 s86, v254, 38
	v_readlane_b32 s82, v254, 45
	v_readlane_b32 s34, v255, 17
	s_barrier
	v_readlane_b32 s83, v254, 46

.LBB0_956:
	s_andn2_b64 vcc, exec, s[6:7]
	s_cbranch_vccnz .LBB0_1130
	v_readlane_b32 s6, v254, 50
	s_lshl_b32 s2, s34, 4
	v_readlane_b32 s7, v254, 51
	s_and_b64 s[6:7], s[6:7], exec
	s_cselect_b32 s3, 32, 0
	s_add_i32 s12, s3, s2
	s_lshl_b32 s3, s12, 2
	s_lshl_b32 s6, s12, 1
	s_cmp_le_i32 s6, s72
	s_cselect_b64 s[6:7], -1, 0
	s_cmp_gt_i32 s3, s72
	s_cselect_b64 s[8:9], -1, 0
	v_cndmask_b32_e64 v0, 0, 1, s[6:7]
	s_and_b64 s[10:11], s[8:9], exec
	v_readfirstlane_b32 s3, v0
	s_cselect_b32 s3, s3, 2
	s_lshl_b32 s14, s12, s3
	v_readlane_b32 s10, v253, 3
	s_cmp_ge_i32 s10, s14
	s_waitcnt lgkmcnt(0)
	s_barrier
	s_cbranch_scc1 .LBB0_1130
	s_and_b64 s[6:7], s[6:7], exec
	s_cselect_b32 s10, 2, 1
	s_and_b64 s[6:7], s[8:9], exec
	s_cselect_b32 s15, s10, 4
	v_cvt_f32_ubyte0_e32 v0, s15
	v_rcp_iflag_f32_e32 v0, v0
	v_readlane_b32 s8, v254, 63
	s_cmp_lg_u64 s[46:47], 0
	v_readlane_b32 s9, v255, 0
	v_mul_f32_e32 v0, 0x4f7ffffe, v0
	v_cvt_u32_f32_e32 v0, v0
	s_cselect_b64 s[6:7], -1, 0
	s_cmp_lg_u64 s[8:9], 0
	s_cselect_b64 s[8:9], -1, 0
	s_sub_i32 s10, 0, s15
	v_readfirstlane_b32 s11, v0
	s_mul_i32 s10, s10, s11
	s_mul_hi_u32 s10, s11, s10
	s_add_i32 s16, s11, s10
	v_readlane_b32 s17, v253, 46
	v_readlane_b32 s24, v253, 45
	v_readlane_b32 s25, v253, 3
	s_branch .LBB0_962
